# dilated-attention unit remap (consecutive query blocks per workgroup, neighbours on one XCD, pattern order rotated per workgroup) on top of the nt input loads
# baseline (speedup 1.0000x reference)
.LBB0_478:
	v_readlane_b32 s4, v254, 9
	s_cmp_lt_i32 s4, 3
	s_cselect_b64 s[2:3], -1, 0
	s_and_b64 s[0:1], s[2:3], s[0:1]
	s_andn2_b64 vcc, exec, s[0:1]
	v_readlane_b32 s5, v254, 10
	v_readlane_b32 s6, v254, 11
	v_readlane_b32 s7, v254, 12
	s_cbranch_vccnz .LBB0_515
	v_writelane_b32 v254, s0, 33
	s_waitcnt lgkmcnt(0)
	s_add_u32 s78, s96, 0x5500000
	s_addc_u32 s79, s97, 0
	v_writelane_b32 v254, s1, 34
	v_writelane_b32 v254, s89, 35
	s_mov_b32 s0, s88
	s_mov_b64 s[20:21], s[90:91]
	v_writelane_b32 v254, s0, 36
	s_cmpk_gt_i32 s88, 0x5ff
	s_nop 0
	v_writelane_b32 v254, s1, 37
	s_cbranch_scc1 .LBB0_511
	v_lshlrev_b32_e32 v0, 2, v227
	global_load_dword v8, v0, s[74:75]
	global_load_dword v9, v0, s[76:77]
	s_waitcnt vmcnt(0) lgkmcnt(0)
	v_and_b32_e32 v8, 0x7fffffff, v8
	v_and_b32_e32 v9, 0x7fffffff, v9
	s_nop 1
	v_max_f32_dpp v8, v8, v8 quad_perm:[1,0,3,2] row_mask:0xf bank_mask:0xf
	v_max_f32_dpp v9, v9, v9 quad_perm:[1,0,3,2] row_mask:0xf bank_mask:0xf
	s_nop 1
	v_max_f32_dpp v8, v8, v8 quad_perm:[2,3,0,1] row_mask:0xf bank_mask:0xf
	v_max_f32_dpp v9, v9, v9 quad_perm:[2,3,0,1] row_mask:0xf bank_mask:0xf
	s_nop 1
	v_max_f32_dpp v8, v8, v8 row_half_mirror row_mask:0xf bank_mask:0xf
	v_max_f32_dpp v9, v9, v9 row_half_mirror row_mask:0xf bank_mask:0xf
	s_nop 1
	v_max_f32_dpp v8, v8, v8 row_mirror row_mask:0xf bank_mask:0xf
	v_max_f32_dpp v9, v9, v9 row_mirror row_mask:0xf bank_mask:0xf
	s_nop 1
	v_readlane_b32 s0, v8, 0
	v_readlane_b32 s1, v8, 16
	v_readlane_b32 s2, v8, 32
	v_readlane_b32 s3, v8, 48
	s_max_u32 s0, s0, s1
	s_max_u32 s2, s2, s3
	s_max_u32 s0, s0, s2
	v_readlane_b32 s1, v9, 0
	v_readlane_b32 s2, v9, 16
	v_readlane_b32 s3, v9, 32
	v_readlane_b32 s98, v9, 48
	s_max_u32 s1, s1, s2
	s_max_u32 s3, s3, s98
	s_max_u32 s1, s1, s3
	s_nop 0
	v_mov_b32_e32 v8, s0
	v_mov_b32_e32 v9, s1
	v_readlane_b32 s0, v254, 36
	v_readlane_b32 s1, v254, 37
	s_lshr_b32 s98, s0, 8
	s_and_b32 s99, s0, 0xff
	s_and_b32 s101, s99, 7
	s_lshr_b32 s99, s99, 3
	s_mul_i32 s0, s99, 171
	s_lshr_b32 s0, s0, 9
	s_mul_i32 s0, s0, 3
	s_sub_i32 s0, s99, s0
	s_lshl_b32 s0, s0, 1
	s_add_i32 s98, s98, s0
	s_cmp_ge_u32 s98, 6
	s_cbranch_scc0 .Ldg_nr_a
	s_add_i32 s98, s98, -6
